# SWA (GQA) phase: items renumbered so the 4 query heads sharing a KV head and 8 consecutive q-chunks run on the same XCD in the same round (K/V chunks fetched into one L2 instead of four)
# speedup vs baseline: 1.0068x; 1.0068x over previous
; #define LAS __attribute__((address_space(3)))
; template <int HD, int DV, int HW, int MODE> ...
;     ...
;     const int w = __builtin_amdgcn_readfirstlane(tid >> 6), lane = tid & 63, ql = lane & 31, hh = lane >> 5;
;     const int iw = i0 + 32 * w, x32a = ((lane ^ 32) << 2);
;     LAS unsigned char* Kl = lds; LAS unsigned char* Vl = lds + KB;
;     bf16x8 qf[KS];
;     { const bf16_t* qrow = qp + (tok0 + (size_t)r * (iw + ql)) * ld + 8 * hh;
; #pragma unroll
;       for (int ks = 0; ks < KS; ++ks) qf[ks] = *(const bf16x8*)(qrow + 16 * ks); }
;     f32x16 O[NTV];
; #pragma unroll
;     for (int t = 0; t < NTV; ++t)
; #pragma unroll
;         for (int i = 0; i < 16; ++i) O[t][i] = 0.f;
;     float m = (MODE == 1) ? sink2 : -1e30f, l = (MODE == 1 && hh == 0) ? 1.0f : 0.f;
;     const int pi = (ql & ~12) | ((ql & 4) << 1) | ((ql & 8) >> 1);
;     const LAS unsigned char* kread = Kl + pi * RSK + 16 * hh;
;     const int g16 = lane >> 4, i16 = lane & 15;
;     const LAS unsigned char* vread = Vl + (8 * (g16 >> 1) + (i16 >> 2)) * RSV + (16 * (g16 & 1) + 4 * (i16 & 3)) * 2;
;     u32x4 kreg[KLD], vreg[VLD];
;     auto prefetch = [&](int c) {
;         const int jc = i0 - HW + CR * c;
; #pragma unroll
;         for (int i = 0; i < KLD; ++i) { const int idx = tid + 512 * i, row = idx / KCH, ch = idx % KCH, j = jc + row;
;             kreg[i] = (j >= 0 && j < L) ? *(const u32x4*)(kp + (tok0 + (size_t)r * j) * ld + ch * 8) : (u32x4){0, 0, 0, 0}; }
; #pragma unroll
;         for (int i = 0; i < VLD; ++i) { const int idx = tid + 512 * i, row = idx / VCH, ch = idx % VCH, j = jc + row;
;             vreg[i] = (j >= 0 && j < L) ? *(const u32x4*)(vp + (tok0 + (size_t)r * j) * ld + ch * 8) : (u32x4){0, 0, 0, 0}; }
; __device__ __forceinline__ void swa_attn_phase(const Params& p, LAS unsigned char* lds) {
;     ...
;     for (int it = blockIdx.x; it < 2048; it += gridDim.x) {
;         const int h = it & 15, rest = it >> 4, qc = rest & 31, b = rest >> 5;
;         band_item<64, 64, 128, 1>(PROJ + h * 64, PROJ + 1024 + (h >> 2) * 64, PROJ + 1280 + (h >> 2) * 64, 2560, (size_t)b * SEQ, 1, SEQ, qc * 256, p.swa_sink[h] * LOG2E,
.LBB0_158:
	s_bfe_u32 s48, s21, 0x20003
	s_and_b32 s23, s21, 3
	s_lshl_b32 s23, s23, 2
	s_or_b32 s48, s48, s23
	s_bfe_u32 s23, s21, 0x40005
	s_lshl_b32 s23, s23, 4
	s_or_b32 s48, s48, s23
	s_bfe_u32 s23, s21, 0x10002
	s_lshl_b32 s23, s23, 8
	s_or_b32 s48, s48, s23
	s_and_b32 s23, s21, 0x600
	s_or_b32 s48, s48, s23
	s_and_b32 s4, s48, 15
	s_ashr_i32 s10, s48, 9
	s_lshl_b32 s2, s4, 7
	s_add_u32 s28, s84, s2
	s_addc_u32 s29, s85, 0
	s_lshl_b32 s2, s48, 4
	s_and_b32 s5, s2, 0xc0
	s_lshl_b32 s23, s5, 1
	s_add_u32 s44, s78, s23
	s_addc_u32 s45, s83, 0
	s_ashr_i32 s11, s10, 31
	s_lshl_b64 s[26:27], s[10:11], 13
	s_load_dwordx2 s[10:11], s[0:1], 0x58
	s_and_b32 s48, s2, 0x1f00
	s_lshl_b32 s2, s4, 2
	v_mov_b32_e32 v1, s2
	v_mov_b32_e32 v6, v207
	s_waitcnt lgkmcnt(0)
	global_load_dword v8, v1, s[10:11]
	v_mov_b32_e32 v103, v0
	v_readfirstlane_b32 s2, v6
	s_ashr_i32 s5, s2, 1
	s_andn2_b32 s5, s5, 31
	v_and_b32_e32 v1, 31, v6
	s_add_i32 s22, s5, s48
	v_or_b32_e32 v104, s22, v1
	v_ashrrev_i32_e32 v105, 31, v104
	v_lshl_add_u64 v[96:97], s[26:27], 0, v[104:105]
	s_movk_i32 s2, 0xa00
	v_mad_u64_u32 v[98:99], s[10:11], v96, s2, 0
	v_bfe_u32 v10, v6, 5, 1
	v_mad_i32_i24 v99, v97, s2, v99
	v_lshl_add_u64 v[2:3], v[98:99], 1, s[28:29]
	v_lshlrev_b32_e32 v102, 4, v10
	v_lshl_add_u64 v[2:3], v[2:3], 0, v[102:103]
	global_load_dwordx4 v[76:79], v[2:3], off
	global_load_dwordx4 v[72:75], v[2:3], off offset:32
	global_load_dwordx4 v[68:71], v[2:3], off offset:64
	global_load_dwordx4 v[64:67], v[2:3], off offset:96
	v_ashrrev_i32_e32 v2, 31, v6
	v_lshrrev_b32_e32 v2, 29, v2
	v_add_u32_e32 v2, v6, v2
	v_ashrrev_i32_e32 v7, 3, v2
	v_and_b32_e32 v2, -8, v2
	s_add_i32 s25, s48, 0xffffff80
	v_sub_u32_e32 v9, v6, v2
	v_add_u32_e32 v3, s25, v7
	v_lshlrev_b32_e32 v2, 3, v9
	v_cmp_gt_u32_e32 vcc, s31, v3
	v_mov_b32_e32 v80, 0
	v_or_b32_e32 v14, s26, v3
	v_ashrrev_i32_e32 v3, 31, v2
	v_mov_b32_e32 v84, 0
	v_mov_b32_e32 v85, 0
	v_mov_b32_e32 v86, 0
	v_mov_b32_e32 v87, 0
	s_and_saveexec_b64 s[40:41], vcc
	s_cbranch_execz .LBB0_160
	v_mov_b64_e32 v[4:5], s[44:45]
	v_mad_u64_u32 v[4:5], s[10:11], v14, s38, v[4:5]
	v_mad_i32_i24 v5, s27, v235, v5
	v_lshl_add_u64 v[4:5], v[2:3], 1, v[4:5]
	global_load_dwordx4 v[84:87], v[4:5], off

; #define LAS __attribute__((address_space(3)))
; template <int HD, int DV, int HW, int MODE> ...
;     ...
;     f32x16 O[NTV];
; #pragma unroll
;     for (int t = 0; t < NTV; ++t)
; #pragma unroll
;         for (int i = 0; i < 16; ++i) O[t][i] = 0.f;
;     float m = (MODE == 1) ? sink2 : -1e30f, l = (MODE == 1 && hh == 0) ? 1.0f : 0.f;
;     const int pi = (ql & ~12) | ((ql & 4) << 1) | ((ql & 8) >> 1);
;     const LAS unsigned char* kread = Kl + pi * RSK + 16 * hh;
;     const int g16 = lane >> 4, i16 = lane & 15;
;     const LAS unsigned char* vread = Vl + (8 * (g16 >> 1) + (i16 >> 2)) * RSV + (16 * (g16 & 1) + 4 * (i16 & 3)) * 2;
;     ...
;     for (int c = 0; c < NC; ++c) {
;         const int jc = i0 - HW + CR * c;
.LBB0_168:
	s_or_b64 exec, exec, s[40:41]
	v_and_b32_e32 v13, 63, v6
	v_lshlrev_b32_e32 v100, 3, v10
	v_cmp_gt_u32_e32 vcc, 32, v13
	v_lshlrev_b32_e32 v10, 1, v6
	v_lshrrev_b32_e32 v13, 1, v6
	s_waitcnt vmcnt(0)
	v_mul_f32_e32 v115, 0x3fb8aa3b, v8
	v_and_b32_e32 v8, 19, v6
	v_and_b32_e32 v10, 8, v10
	v_and_b32_e32 v13, 4, v13
	v_or3_b32 v8, v8, v10, v13
	s_movk_i32 s10, 0x90
	v_lshlrev_b64 v[2:3], 1, v[2:3]
	v_mad_u32_u24 v117, v8, s10, 0
	v_lshrrev_b32_e32 v8, 2, v6
	v_lshl_add_u64 v[106:107], s[44:45], 0, v[2:3]
	v_lshl_add_u64 v[110:111], s[42:43], 0, v[2:3]
	v_mul_lo_u32 v2, v7, s10
	v_and_b32_e32 v8, 11, v8
	s_movk_i32 s2, 0xc0
	v_add_u32_e32 v114, 0, v2
	v_mul_lo_u32 v2, v11, s10
	v_mad_u32_u24 v103, v8, s2, 0
	v_and_b32_e32 v8, 16, v6
	v_lshlrev_b32_e32 v6, 2, v6
	v_add_u32_e32 v116, 0, v2
	s_lshl_b32 s46, s4, 6
	s_mov_b32 s4, s48
	v_and_or_b32 v6, v6, 12, v8
	v_lshlrev_b64 v[4:5], 1, v[4:5]
	v_lshlrev_b32_e32 v120, 4, v9
	v_lshlrev_b32_e32 v121, 4, v12
	v_mad_u64_u32 v[16:17], s[10:11], v7, 48, v[114:115]
	v_mad_u64_u32 v[18:19], s[10:11], v11, 48, v[116:117]
	v_add_u32_e32 v2, s5, v1
	v_sub_u32_e32 v1, v100, v1
	v_mov_b32_e32 v14, v0
	v_mov_b32_e32 v15, v0
	v_lshlrev_b32_e32 v105, 1, v6
	v_lshl_add_u64 v[108:109], s[44:45], 0, v[4:5]
	v_lshl_add_u64 v[112:113], s[42:43], 0, v[4:5]
	v_add_u32_e32 v122, s4, v11
	v_add_u32_e32 v123, s4, v7
	v_sub_u32_e32 v124, v2, v100
	v_subrev_u32_e32 v125, s5, v1
	v_mov_b32_e32 v1, v0
	v_mov_b32_e32 v2, v0
	v_mov_b32_e32 v3, v0
	v_mov_b32_e32 v4, v0
	v_mov_b32_e32 v5, v0
	v_mov_b32_e32 v6, v0
	v_mov_b32_e32 v7, v0
	v_mov_b32_e32 v8, v0
	v_mov_b32_e32 v9, v0
	v_mov_b32_e32 v10, v0
	v_mov_b32_e32 v11, v0
	v_mov_b32_e32 v12, v0
	v_mov_b32_e32 v13, v0
	v_add_u32_e32 v118, v16, v120
	v_add_u32_e32 v119, v18, v121
	v_mov_b64_e32 v[30:31], v[14:15]
	v_mov_b64_e32 v[46:47], v[14:15]
	v_cndmask_b32_e64 v101, 0, 1.0, vcc
	s_add_i32 s53, s22, 0xffffff80
	s_add_i32 s52, s22, 0x9f
	s_add_i32 s49, s22, 0xffffff9f
	s_add_i32 s47, s22, 0x61
	s_mov_b32 s5, 0
	s_mov_b32 s22, 0
	v_mov_b64_e32 v[28:29], v[12:13]
	v_mov_b64_e32 v[26:27], v[10:11]
	v_mov_b64_e32 v[24:25], v[8:9]
	v_mov_b64_e32 v[22:23], v[6:7]
	v_mov_b64_e32 v[20:21], v[4:5]
	v_mov_b64_e32 v[18:19], v[2:3]
	v_mov_b64_e32 v[16:17], v[0:1]
	v_mov_b64_e32 v[44:45], v[12:13]
	v_mov_b64_e32 v[42:43], v[10:11]
	v_mov_b64_e32 v[40:41], v[8:9]
	v_mov_b64_e32 v[38:39], v[6:7]
	v_mov_b64_e32 v[36:37], v[4:5]
	v_mov_b64_e32 v[34:35], v[2:3]
	v_mov_b64_e32 v[32:33], v[0:1]
	s_branch .LBB0_171
